# P=80 with KSPLIT 1024
# speedup vs baseline: 1.0061x; 1.0061x over previous
; __global__ void __launch_bounds__(NWAVES * 64, 2) hybrid_fwd(Args A) {
;     ...
;             if (s == 0 && EN(1)) { pg8::Gemm g{WS_PTR(const bf16, WS_HB), WS_PTR(const bf16, WS_WINT) + (size_t)l * DINP * D, M, DINP, D, D}; pg8::StaticOrder S; S.init(M, DINP, C.G, C.bid);
;                 pg8::EpiU E{WS_PTR(bf16, WS_U), WS_PTR(const float, WS_SS) + (size_t)l * M};
;                 pg8::gemm_phase<pg8::EpiU, pg8::StaticOrder, G1_ALIGN, G1_SP2>(C.lds, g, S, E); }
;             else if (s == 1 && EN(2)) phase_prep(A, C, l);
;             else if ((s == 2 && EN(3)) || (s == 3 && EN(4)) || (s == 4 && EN(5))) {
;                 const bool split = C.G >= 192; bool go = (s == 4); int k0 = split ? KSPLIT : 0, kl = D - k0, gg = C.G, cc = C.bid, mrows = M; size_t roff = 0;
;                 if (s == 2) { go = phase_mixers(A, C, l, rep ? DUP_UN : 7); k0 = 0; kl = KSPLIT; gg = C.G - 128; cc = C.bid - 128; mrows = MP; }
;                 if (s == 3) { phase_post(A, C, l, split ? 8 : 0); go = split && C.bid < 8 && !rep; k0 = 0; kl = KSPLIT; gg = 8; cc = C.bid; mrows = MS; roff = (size_t)MP * D; }
;                 if (go) { pg8::Gemm g{WS_PTR(const bf16, WS_XN) + roff + k0, WS_PTR(const bf16, WS_WOUTT) + (size_t)l * D * D + k0, mrows, D, kl, D}; pg8::StaticOrder S; S.init(mrows, D, gg, cc);
;                     const bool first = (l == 0) && (s != 4 || !split);
;                     float* Hout = ((rep && s == 4) ? WS_PTR(float, WS_U) : A.out) + roff;
;                     pg8::EpiResN E{Hout, first ? (s == 3 ? A.in[I_XS] : A.in[I_XP]) : Hout, first ? A.in[I_XS] - (size_t)MP * D : Hout, WS_PTR(bf16, WS_HB), WS_PTR(float, WS_SS) + (size_t)(l + 1) * M, s == 4 && !rep};
;                     pg8::gemm_phase<pg8::EpiResN, pg8::StaticOrder, G2_ALIGN, true>(C.lds, g, S, E); }
.LBB0_14:
	v_readlane_b32 s12, v253, 0
	s_cmpk_lt_i32 s12, 0xb16
	s_cselect_b64 s[2:3], -1, 0
	v_writelane_b32 v253, s2, 11
	s_load_dword s13, s[0:1], 0xe8
	s_load_dwordx4 s[16:19], s[0:1], 0xc0
	s_load_dwordx2 s[14:15], s[0:1], 0xd0
	v_writelane_b32 v253, s3, 12
	s_ashr_i32 s2, s12, 31
	v_writelane_b32 v253, s2, 13
	s_lshr_b32 s2, s2, 29
	s_add_i32 s2, s12, s2
	s_ashr_i32 s9, s2, 3
	s_and_b32 s2, s2, -8
	s_sub_i32 s10, s12, s2
	s_mul_i32 s2, s10, 0x162
	s_add_i32 s11, s2, 6
	s_waitcnt lgkmcnt(0)
	s_ashr_i32 s2, s13, 31
	s_cmpk_lt_i32 s13, 0xc0
	v_writelane_b32 v253, s2, 14
	s_cselect_b64 s[2:3], -1, 0
	v_writelane_b32 v253, s2, 15
	s_cmpk_gt_i32 s13, 0xbf
	s_load_dwordx16 s[80:95], s[0:1], 0x0
	v_writelane_b32 v253, s3, 16
	s_cselect_b64 s[2:3], -1, 0
	s_and_b64 s[6:7], s[2:3], exec
	s_cselect_b32 s7, 8, 0
	s_cselect_b32 s6, 0x400, 0
	v_writelane_b32 v253, s7, 17
	v_writelane_b32 v253, s6, 18
	s_sub_i32 s6, 0x800, s6
	v_writelane_b32 v253, s6, 19
	s_add_u32 s6, s18, 0x10692000
	v_writelane_b32 v253, s6, 20
	s_addc_u32 s6, s19, 0
	v_writelane_b32 v253, s6, 21
	s_add_u32 s6, s18, 0x10200000
	v_writelane_b32 v253, s6, 22
	s_addc_u32 s6, s19, 0
	v_writelane_b32 v253, s6, 23
	s_add_u32 s6, s18, 0x10bb6000
	v_writelane_b32 v253, s6, 24
	s_addc_u32 s6, s19, 0
	v_writelane_b32 v253, s6, 25
	s_add_u32 s6, s18, 0x10492000
	v_writelane_b32 v253, s6, 26
	s_addc_u32 s6, s19, 0
	s_waitcnt lgkmcnt(0)
	s_cmp_eq_u64 s[92:93], 0
	v_writelane_b32 v253, s6, 27
	s_cselect_b64 s[6:7], -1, 0
	v_writelane_b32 v253, s6, 28
	s_cmp_lg_u64 s[92:93], 0
	s_load_dwordx16 s[36:51], s[0:1], 0x40
	v_writelane_b32 v253, s7, 29
	s_cselect_b64 s[6:7], -1, 0
	v_writelane_b32 v253, s6, 30
	v_mov_b32_e32 v207, 0x260
	v_mov_b32_e32 v229, 0x3727c5ac
	v_writelane_b32 v253, s7, 31
	s_add_u32 s6, s14, 0x8000
	v_writelane_b32 v253, s6, 32
	s_addc_u32 s6, s15, 0
	v_writelane_b32 v253, s6, 33
	s_add_i32 s6, s13, 0xffffff80
	v_writelane_b32 v253, s6, 34
	s_add_i32 s6, s12, 0xffffff80
	s_cmp_lt_i32 s12, 8
	v_writelane_b32 v253, s6, 35
	s_cselect_b64 s[6:7], -1, 0
	s_and_b64 s[2:3], s[6:7], s[2:3]
	v_writelane_b32 v253, s2, 36
	v_mov_b32_e32 v252, 1
	v_mov_b32_e32 v251, 0x7f800000
	v_writelane_b32 v253, s3, 37
	s_add_u32 s2, s82, 0xf0000000
	v_writelane_b32 v253, s2, 38
	s_addc_u32 s2, s83, -1
	s_cmp_lg_u64 s[94:95], 0
	v_writelane_b32 v253, s2, 39
	s_cselect_b64 s[2:3], -1, 0
	v_writelane_b32 v253, s2, 40
	s_cmp_lg_u32 s26, 2
	v_mov_b32_e32 v142, 0x41b17218
	v_writelane_b32 v253, s3, 41
	s_cselect_b64 s[2:3], -1, 0
	v_writelane_b32 v253, s2, 42
	v_mov_b32_e32 v143, 0x3000
	s_movk_i32 s33, 0x7fff
	v_writelane_b32 v253, s3, 43
	s_add_u32 s2, s14, 0x4200
	s_addc_u32 s3, s15, 0
	v_writelane_b32 v253, s2, 44
	s_mov_b32 s96, 0xffff0000
	s_mov_b32 s97, 0x3fb8aa3b
	v_writelane_b32 v253, s3, 45
	s_add_u32 s2, s14, 0x4400
	s_addc_u32 s3, s15, 0
	v_writelane_b32 v253, s2, 46
	s_mov_b32 s20, 0xbfb8aa3b
	s_mov_b32 s21, 0xb2a5705f
	v_writelane_b32 v253, s3, 47
	s_add_u32 s2, s14, 0x4500
	s_addc_u32 s3, s15, 0
	v_writelane_b32 v253, s2, 48
	s_mov_b32 s28, 0x42ce8ed0
	s_mov_b32 s29, 0xc2b17218
	v_writelane_b32 v253, s3, 49
	s_add_u32 s2, s14, 0x4600
	s_addc_u32 s3, s15, 0
	v_writelane_b32 v253, s2, 50
	s_mov_b32 s34, 0x7f800000
	s_mov_b32 s35, 0x800000
	v_writelane_b32 v253, s3, 51
	s_add_u32 s2, s14, 0x4700
	s_addc_u32 s3, s15, 0
	v_writelane_b32 v253, s2, 52
	s_mov_b64 s[22:23], 0x80
	s_nop 0
	v_writelane_b32 v253, s3, 53
	s_add_u32 s2, s14, 0x4800
	s_addc_u32 s3, s15, 0
	v_writelane_b32 v253, s2, 54
	s_nop 1
	v_writelane_b32 v253, s3, 55
	s_add_u32 s2, s14, 0x4900
	s_addc_u32 s3, s15, 0
	v_writelane_b32 v253, s2, 56
	s_nop 1
	v_writelane_b32 v253, s3, 57
	s_add_u32 s2, s14, 0x4a00
	s_addc_u32 s3, s15, 0
	v_writelane_b32 v253, s2, 58
	s_nop 1
	v_writelane_b32 v253, s3, 59
	s_add_u32 s2, s14, 0x4b00
	s_addc_u32 s3, s15, 0
	v_writelane_b32 v253, s2, 60
	s_nop 1
	v_writelane_b32 v253, s3, 61
	s_add_u32 s2, s14, 0x4c00
	s_addc_u32 s3, s15, 0
	v_writelane_b32 v253, s2, 62
	s_nop 1
	v_writelane_b32 v253, s3, 63
	s_add_u32 s2, s14, 0x4d00
	s_addc_u32 s3, s15, 0
	v_writelane_b32 v254, s2, 0
	s_nop 1
	v_writelane_b32 v254, s3, 1
	s_add_u32 s2, s14, 0x4e00
	s_addc_u32 s3, s15, 0
	v_writelane_b32 v254, s2, 2
	s_nop 1
	v_writelane_b32 v254, s3, 3
	s_add_u32 s2, s14, 0x4f00
	s_addc_u32 s3, s15, 0
	v_writelane_b32 v254, s2, 4
	s_nop 1
	v_writelane_b32 v254, s3, 5
	s_add_u32 s2, s14, 0x5000
	s_addc_u32 s3, s15, 0
	v_writelane_b32 v254, s2, 6
	s_nop 1
	v_writelane_b32 v254, s3, 7
	s_add_u32 s2, s14, 0x5100
	s_addc_u32 s3, s15, 0
	v_writelane_b32 v254, s2, 8
	s_nop 1
	v_writelane_b32 v254, s3, 9
	s_add_u32 s2, s14, 0x5200
	s_addc_u32 s3, s15, 0
	v_writelane_b32 v254, s2, 10
	s_nop 1
	v_writelane_b32 v254, s3, 11
	s_add_u32 s2, s14, 0x5300
	s_addc_u32 s3, s15, 0
	v_writelane_b32 v254, s2, 12
	s_cmp_eq_u32 s8, 15
	s_nop 0
	v_writelane_b32 v254, s3, 13
	s_cselect_b64 s[2:3], -1, 0
	v_writelane_b32 v254, s2, 14
	s_cmp_eq_u32 s8, 14
	s_nop 0
	v_writelane_b32 v254, s3, 15
	s_cselect_b64 s[2:3], -1, 0
	v_writelane_b32 v254, s2, 16
	s_cmp_eq_u32 s8, 13
	s_nop 0
	v_writelane_b32 v254, s3, 17
	s_cselect_b64 s[2:3], -1, 0
	v_writelane_b32 v254, s2, 18
; __device__ __forceinline__ unsigned xb_ld(unsigned* p)              { return __hip_atomic_load(p, __ATOMIC_RELAXED, __HIP_MEMORY_SCOPE_AGENT); }
;     __host__ __device__ bool next(int i, Unit& u) const {
;         const long L = (long)i * G + c; if (L >= nwg) return false;
;         int wgid = (int)L; { const int q = nwg / NXCD, r = nwg % NXCD, xcd = wgid % NXCD, off = wgid / NXCD; wgid = (xcd < r ? xcd * (q + 1) : r * (q + 1) + (xcd - r) * q) + off; }
;         const int nig = WGM * nN, gid = wgid / nig, fm = gid * WGM, gsz = (nM - fm) < WGM ? (nM - fm) : WGM;
;         u.pm = fm + ((wgid % nig) % gsz); u.pn = (wgid % nig) / gsz; return true;
; __device__ __forceinline__ void xcd_barrier_complete(unsigned* bar, unsigned x, unsigned& nloc, unsigned& nx) {
;     const unsigned G = gridDim.x * gridDim.y * gridDim.z;
;     unsigned sum, cnt, mine, sp = 0u;
;     for (;;) {
;         sum = 0u; cnt = 0u; mine = 0u;
; #pragma unroll
;         for (unsigned j = 0; j < 16; ++j) { const unsigned c = xb_ld(&bar[XB_XCNT(j)]); sum += c; cnt += (c > 0u) ? 1u : 0u; mine = (j == x) ? c : mine; }
;         if (sum == G) break;
;         __builtin_amdgcn_s_sleep(1);
;         if ((++sp & 255u) == 0u) { if (xb_ld(&bar[XB_TMO])) break; if (sp > XB_SPIN_CAP) { atomicAdd(&bar[XB_TMO], 1u); break; } }
;     }
;     nloc = mine > 0u ? mine : 1u; nx = cnt > 0u ? cnt : 1u;
	s_cmp_eq_u32 s8, 12
	s_nop 0
	v_writelane_b32 v254, s3, 19
	s_cselect_b64 s[2:3], -1, 0
	v_writelane_b32 v254, s2, 20
	s_cmp_eq_u32 s8, 11
	s_nop 0
	v_writelane_b32 v254, s3, 21
	s_cselect_b64 s[2:3], -1, 0
	v_writelane_b32 v254, s2, 22
	s_cmp_eq_u32 s8, 10
	s_nop 0
	v_writelane_b32 v254, s3, 23
	s_cselect_b64 s[2:3], -1, 0
	v_writelane_b32 v254, s2, 24
	s_cmp_eq_u32 s8, 9
	s_nop 0
	v_writelane_b32 v254, s3, 25
	s_cselect_b64 s[2:3], -1, 0
	v_writelane_b32 v254, s2, 26
	s_cmp_eq_u32 s8, 8
	s_nop 0
	v_writelane_b32 v254, s3, 27
	s_cselect_b64 s[2:3], -1, 0
	v_writelane_b32 v254, s2, 28
	s_cmp_eq_u32 s8, 7
	s_nop 0
	v_writelane_b32 v254, s3, 29
	s_cselect_b64 s[2:3], -1, 0
	v_writelane_b32 v254, s2, 30
	s_cmp_eq_u32 s8, 6
	s_nop 0
	v_writelane_b32 v254, s3, 31
	s_cselect_b64 s[2:3], -1, 0
	v_writelane_b32 v254, s2, 32
	s_cmp_eq_u32 s8, 5
	s_nop 0
	v_writelane_b32 v254, s3, 33
	s_cselect_b64 s[2:3], -1, 0
	v_writelane_b32 v254, s2, 34
	s_cmp_eq_u32 s8, 4
	s_nop 0
	v_writelane_b32 v254, s3, 35
	s_cselect_b64 s[2:3], -1, 0
	v_writelane_b32 v254, s2, 36
	s_cmp_eq_u32 s8, 3
	s_nop 0
	v_writelane_b32 v254, s3, 37
	s_cselect_b64 s[2:3], -1, 0
	v_writelane_b32 v254, s2, 38
	s_cmp_eq_u32 s8, 2
	s_nop 0
	v_writelane_b32 v254, s3, 39
	s_cselect_b64 s[2:3], -1, 0
	v_writelane_b32 v254, s2, 40
	s_cmp_eq_u32 s8, 1
	s_nop 0
	v_writelane_b32 v254, s3, 41
	s_cselect_b64 s[2:3], -1, 0
	v_writelane_b32 v254, s2, 42
	s_cmp_eq_u32 s8, 0
	s_nop 0
	v_writelane_b32 v254, s3, 43
	s_cselect_b64 s[2:3], -1, 0
	v_writelane_b32 v254, s2, 44
	s_nop 1
	v_writelane_b32 v254, s3, 45
	s_lshl_b32 s2, s8, 8
	s_add_u32 s2, s4, s2
	s_addc_u32 s3, s5, 0
	s_add_u32 s4, s2, 0x1400
	s_addc_u32 s5, s3, 0
	v_writelane_b32 v254, s4, 46
	s_add_u32 s2, s2, 0x2400
	s_addc_u32 s3, s3, 0
	v_writelane_b32 v254, s5, 47
	v_writelane_b32 v254, s2, 48
	s_nop 1
	v_writelane_b32 v254, s3, 49
	s_add_u32 s2, s14, 0x7400
	s_addc_u32 s3, s15, 0
	v_writelane_b32 v254, s2, 50
	s_nop 1
	v_writelane_b32 v254, s3, 51
	s_add_u32 s2, s14, 0x7500
	s_addc_u32 s3, s15, 0
	v_writelane_b32 v254, s2, 52
	s_cmp_lt_i32 s10, 6
	s_mulk_i32 s10, 0x163
	v_writelane_b32 v254, s3, 53
	s_cselect_b32 s2, s10, s11
	s_add_i32 s2, s2, s9
	s_mul_hi_i32 s3, s2, 0x2e8ba2e9
	s_lshr_b32 s4, s3, 31
	s_ashr_i32 s3, s3, 5
	s_add_i32 s3, s3, s4
	s_mul_i32 s4, s3, 0xb0
	s_lshl_b32 s5, s3, 3
	s_sub_i32 s4, s2, s4
	s_sub_i32 s2, 0x81, s5
	s_min_u32 s6, s2, 8
	v_cvt_f32_ubyte0_e32 v2, s6
	v_cvt_f32_i32_e32 v1, s4
	v_rcp_iflag_f32_e32 v3, v2
	s_ashr_i32 s2, s4, 30
	s_or_b32 s7, s2, 1
	v_mul_f32_e32 v3, v1, v3
	v_trunc_f32_e32 v3, v3
	v_fma_f32 v1, -v3, v2, v1
	v_cmp_ge_f32_e64 s[2:3], |v1|, v2
	v_lshrrev_b32_e32 v1, 20, v0
	v_lshrrev_b32_e32 v0, 10, v0
	v_or_b32_e32 v0, v0, v1
	v_cvt_i32_f32_e32 v1, v3
	s_and_b64 s[2:3], s[2:3], exec
	s_movk_i32 s2, 0x3ff
	v_and_or_b32 v0, v0, s2, v185
	s_cselect_b32 s2, s7, 0
	v_readfirstlane_b32 s3, v1
	s_add_i32 s2, s3, s2
	s_mul_i32 s3, s2, s6
	s_sub_i32 s3, s4, s3
	s_sext_i32_i16 s3, s3
	s_add_i32 s3, s5, s3
	v_writelane_b32 v254, s3, 54
	s_sext_i32_i16 s2, s2
	v_writelane_b32 v254, s2, 55
	s_add_u32 s2, s14, 0xfc54300
	s_addc_u32 s3, s15, 0
	v_writelane_b32 v254, s2, 56
	v_mov_b32_e32 v1, 0
	v_mov_b32_e32 v98, v1
	v_writelane_b32 v254, s3, 57
	s_add_u32 s2, s14, 0xfc3c000
	v_writelane_b32 v254, s2, 58
	s_addc_u32 s2, s15, 0
	v_writelane_b32 v254, s2, 59
	s_add_i32 s2, 0, 0xd000
	v_writelane_b32 v254, s2, 60
	s_add_i32 s2, 0, 0x3cf0
	v_writelane_b32 v254, s2, 61
	s_mov_b32 s3, 0
	v_writelane_b32 v254, s2, 62
	v_mov_b32_e32 v99, v1
	v_mov_b32_e32 v100, v1
	v_writelane_b32 v254, s3, 63
	v_cmp_eq_u32_e64 s[2:3], 0, v185
	v_mov_b32_e32 v101, v1
	s_mov_b32 s4, 0x3f317217
	v_writelane_b32 v255, s2, 0
	s_mov_b32 s5, 0xc2ce8ed0
	s_mov_b32 s6, 0x42b17218
	v_writelane_b32 v255, s3, 1
	v_cmp_eq_u32_e64 s[2:3], 0, v0
	s_mov_b32 s7, 0xf800000
	s_nop 0
	v_writelane_b32 v255, s2, 2
	s_nop 1
	v_writelane_b32 v255, s3, 3
	s_waitcnt lgkmcnt(0)
	v_writelane_b32 v255, s36, 4
	s_nop 1
	v_writelane_b32 v255, s37, 5
	v_writelane_b32 v255, s38, 6
	v_writelane_b32 v255, s39, 7
	v_writelane_b32 v255, s40, 8
	v_writelane_b32 v255, s41, 9
	v_writelane_b32 v255, s42, 10
	v_writelane_b32 v255, s43, 11
	v_writelane_b32 v255, s44, 12
	v_writelane_b32 v255, s45, 13
	v_writelane_b32 v255, s46, 14
	v_writelane_b32 v255, s47, 15
	v_writelane_b32 v255, s48, 16
	v_writelane_b32 v255, s49, 17
	v_writelane_b32 v255, s50, 18
	v_writelane_b32 v255, s51, 19
	s_load_dwordx16 s[36:51], s[0:1], 0x80
	s_waitcnt lgkmcnt(0)
	v_writelane_b32 v255, s36, 20
	s_nop 1
	v_writelane_b32 v255, s37, 21
	v_writelane_b32 v255, s38, 22
	v_writelane_b32 v255, s39, 23
	v_writelane_b32 v255, s40, 24
	v_writelane_b32 v255, s41, 25
	v_writelane_b32 v255, s42, 26
	v_writelane_b32 v255, s43, 27
	v_writelane_b32 v255, s44, 28
	v_writelane_b32 v255, s45, 29
	v_writelane_b32 v255, s46, 30
	v_writelane_b32 v255, s47, 31
	v_writelane_b32 v255, s48, 32
	v_writelane_b32 v255, s49, 33
	v_writelane_b32 v255, s50, 34
	v_writelane_b32 v255, s51, 35
	s_mov_b32 s98, 0
	v_writelane_b32 v255, s98, 61
	v_writelane_b32 v255, s98, 62
	v_writelane_b32 v255, s98, 63
	s_branch .LBB0_19

; __global__ void __launch_bounds__(NWAVES * 64, 2) hybrid_fwd(Args A) {
;     ...
;                 if (s == 2) { go = phase_mixers(A, C, l, rep ? DUP_UN : 7); k0 = 0; kl = KSPLIT; gg = C.G - 128; cc = C.bid - 128; mrows = MP; }
;                 if (s == 3) { phase_post(A, C, l, split ? 8 : 0); go = split && C.bid < 8 && !rep; k0 = 0; kl = KSPLIT; gg = 8; cc = C.bid; mrows = MS; roff = (size_t)MP * D; }
;                 if (go) { pg8::Gemm g{WS_PTR(const bf16, WS_XN) + roff + k0, WS_PTR(const bf16, WS_WOUTT) + (size_t)l * D * D + k0, mrows, D, kl, D}; pg8::StaticOrder S; S.init(mrows, D, gg, cc);
.LBB0_1181:
.LBB0_1182:
	s_mov_b32 s8, 0
	s_movk_i32 s3, 0x400
	s_movk_i32 s11, 0x50
	v_readlane_b32 s30, v253, 35
	v_readlane_b32 s17, v253, 34

; __global__ void __launch_bounds__(NWAVES * 64, 2) hybrid_fwd(Args A) {
;     ...
;                 if (s == 3) { phase_post(A, C, l, split ? 8 : 0); go = split && C.bid < 8 && !rep; k0 = 0; kl = KSPLIT; gg = 8; cc = C.bid; mrows = MS; roff = (size_t)MP * D; }
;                 if (go) { pg8::Gemm g{WS_PTR(const bf16, WS_XN) + roff + k0, WS_PTR(const bf16, WS_WOUTT) + (size_t)l * D * D + k0, mrows, D, kl, D}; pg8::StaticOrder S; S.init(mrows, D, gg, cc);
.LBB0_1188:
	v_readlane_b32 s52, v253, 36
	s_mov_b32 s8, 0
	s_movk_i32 s3, 0x400
	s_mov_b32 s17, 8
	s_mov_b32 s11, 1
	s_mov_b64 s[40:41], 0x4000000
	v_readlane_b32 s30, v253, 0
	v_readlane_b32 s53, v253, 37
